# neighbourhood-attention bias select: counted lgkmcnt(15..0) ladder instead of one lgkmcnt(0) before the 16 selects
# speedup vs baseline: 1.0136x; 1.0067x over previous
;     ...
;             if (biased) {
;                 const int drow = (kr0 + t - qr + 7) * 32;
;                 int qcl = qc, csl = cs; asm volatile("" : "+v"(qcl), "+v"(csl));
.LBB0_476:
	s_andn2_b64 vcc, exec, s[2:3]
	s_mov_b64 s[48:49], 0
	s_cbranch_vccnz .LBB0_510
	v_mov_b32_e32 v114, v192
	v_mov_b32_e32 v176, v193
	s_add_i32 s4, s70, s71

; __device__ __forceinline__ int crow(int r, int h) { return (r & 3) + 8 * (r >> 2) + 4 * h; }
;     ...
;                     const int k0 = crow(r, h2), k1 = k0 + 32;
;                     int d0 = k0 - qcl + 15, d1 = k1 - qcl + 15; d0 = d0 < 0 ? 0 : (d0 > 30 ? 30 : d0); d1 = d1 < 0 ? 0 : (d1 > 30 ? 30 : d1);
;                     const float b0 = rpbL[drow + d0], b1 = rpbL[drow + d1];
	v_sub_u32_e32 v166, v188, v114
	v_lshl_add_u32 v166, v166, 2, s4
	v_add_u32_e32 v166, 0xafbc, v166

; __device__ __forceinline__ int crow(int r, int h) { return (r & 3) + 8 * (r >> 2) + 4 * h; }
;     ...
;                 for (int r = 0; r < 16; ++r) {
;                     const int k0 = crow(r, h2), k1 = k0 + 32;
;                     int d0 = k0 - qcl + 15, d1 = k1 - qcl + 15; d0 = d0 < 0 ? 0 : (d0 > 30 ? 30 : d0); d1 = d1 < 0 ? 0 : (d1 > 30 ? 30 : d1);
;                     const float b0 = rpbL[drow + d0], b1 = rpbL[drow + d1];
;                     s0[r] = ((unsigned)(k0 - csl) < 16u) ? s0[r] * C2S + b0 * LOG2E : -1e30f;
	ds_read_b32 v106, v166
	ds_read_b32 v107, v166 offset:4
	ds_read_b32 v108, v166 offset:8
	ds_read_b32 v109, v166 offset:12
	ds_read_b32 v110, v166 offset:32
	ds_read_b32 v111, v166 offset:36
	ds_read_b32 v112, v166 offset:40
	ds_read_b32 v113, v166 offset:44
	ds_read_b32 v116, v166 offset:64
	ds_read_b32 v118, v166 offset:68
	ds_read_b32 v120, v166 offset:72
	ds_read_b32 v122, v166 offset:76
	ds_read_b32 v124, v166 offset:96
	ds_read_b32 v126, v166 offset:100
	ds_read_b32 v128, v166 offset:104
	ds_read_b32 v164, v166 offset:108
	s_waitcnt lgkmcnt(15)
	v_sub_u32_e32 v168, v188, v176
	v_cmp_gt_u32_e32 vcc, 16, v168
	v_mul_f32_e32 v98, s20, v48
	v_mul_f32_e32 v106, s21, v106
	v_add_f32_e32 v98, v98, v106
	v_cndmask_b32_e32 v98, v202, v98, vcc

; __device__ __forceinline__ int crow(int r, int h) { return (r & 3) + 8 * (r >> 2) + 4 * h; }
;     ...
;                     const int k0 = crow(r, h2), k1 = k0 + 32;
;                     int d0 = k0 - qcl + 15, d1 = k1 - qcl + 15; d0 = d0 < 0 ? 0 : (d0 > 30 ? 30 : d0); d1 = d1 < 0 ? 0 : (d1 > 30 ? 30 : d1);
;                     const float b0 = rpbL[drow + d0], b1 = rpbL[drow + d1];
;                     s0[r] = ((unsigned)(k0 - csl) < 16u) ? s0[r] * C2S + b0 * LOG2E : -1e30f;
	s_waitcnt lgkmcnt(14)
	v_sub_u32_e32 v168, v212, v176
	v_cmp_gt_u32_e32 vcc, 16, v168
	v_mul_f32_e32 v99, s20, v49
	v_mul_f32_e32 v107, s21, v107
	v_add_f32_e32 v99, v99, v107
	v_cndmask_b32_e32 v99, v202, v99, vcc

; __device__ __forceinline__ int crow(int r, int h) { return (r & 3) + 8 * (r >> 2) + 4 * h; }
;     ...
;                     const int k0 = crow(r, h2), k1 = k0 + 32;
;                     int d0 = k0 - qcl + 15, d1 = k1 - qcl + 15; d0 = d0 < 0 ? 0 : (d0 > 30 ? 30 : d0); d1 = d1 < 0 ? 0 : (d1 > 30 ? 30 : d1);
;                     const float b0 = rpbL[drow + d0], b1 = rpbL[drow + d1];
;                     s0[r] = ((unsigned)(k0 - csl) < 16u) ? s0[r] * C2S + b0 * LOG2E : -1e30f;
	s_waitcnt lgkmcnt(13)
	v_sub_u32_e32 v168, v214, v176
	v_cmp_gt_u32_e32 vcc, 16, v168
	v_mul_f32_e32 v100, s20, v50
	v_mul_f32_e32 v108, s21, v108
	v_add_f32_e32 v100, v100, v108
	v_cndmask_b32_e32 v100, v202, v100, vcc

; __device__ __forceinline__ int crow(int r, int h) { return (r & 3) + 8 * (r >> 2) + 4 * h; }
;     ...
;                     const int k0 = crow(r, h2), k1 = k0 + 32;
;                     int d0 = k0 - qcl + 15, d1 = k1 - qcl + 15; d0 = d0 < 0 ? 0 : (d0 > 30 ? 30 : d0); d1 = d1 < 0 ? 0 : (d1 > 30 ? 30 : d1);
;                     const float b0 = rpbL[drow + d0], b1 = rpbL[drow + d1];
;                     s0[r] = ((unsigned)(k0 - csl) < 16u) ? s0[r] * C2S + b0 * LOG2E : -1e30f;
	s_waitcnt lgkmcnt(12)
	v_sub_u32_e32 v168, v216, v176
	v_cmp_gt_u32_e32 vcc, 16, v168
	v_mul_f32_e32 v101, s20, v51
	v_mul_f32_e32 v109, s21, v109
	v_add_f32_e32 v101, v101, v109
	v_cndmask_b32_e32 v101, v202, v101, vcc

; __device__ __forceinline__ int crow(int r, int h) { return (r & 3) + 8 * (r >> 2) + 4 * h; }
;     ...
;                     const int k0 = crow(r, h2), k1 = k0 + 32;
;                     int d0 = k0 - qcl + 15, d1 = k1 - qcl + 15; d0 = d0 < 0 ? 0 : (d0 > 30 ? 30 : d0); d1 = d1 < 0 ? 0 : (d1 > 30 ? 30 : d1);
;                     const float b0 = rpbL[drow + d0], b1 = rpbL[drow + d1];
;                     s0[r] = ((unsigned)(k0 - csl) < 16u) ? s0[r] * C2S + b0 * LOG2E : -1e30f;
	s_waitcnt lgkmcnt(11)
	v_sub_u32_e32 v168, v218, v176
	v_cmp_gt_u32_e32 vcc, 16, v168
	v_mul_f32_e32 v102, s20, v52
	v_mul_f32_e32 v110, s21, v110
	v_add_f32_e32 v102, v102, v110
	v_cndmask_b32_e32 v102, v202, v102, vcc

; __device__ __forceinline__ int crow(int r, int h) { return (r & 3) + 8 * (r >> 2) + 4 * h; }
;     ...
;                     const int k0 = crow(r, h2), k1 = k0 + 32;
;                     int d0 = k0 - qcl + 15, d1 = k1 - qcl + 15; d0 = d0 < 0 ? 0 : (d0 > 30 ? 30 : d0); d1 = d1 < 0 ? 0 : (d1 > 30 ? 30 : d1);
;                     const float b0 = rpbL[drow + d0], b1 = rpbL[drow + d1];
;                     s0[r] = ((unsigned)(k0 - csl) < 16u) ? s0[r] * C2S + b0 * LOG2E : -1e30f;
	s_waitcnt lgkmcnt(10)
	v_sub_u32_e32 v168, v220, v176
	v_cmp_gt_u32_e32 vcc, 16, v168
	v_mul_f32_e32 v103, s20, v53
	v_mul_f32_e32 v111, s21, v111
	v_add_f32_e32 v103, v103, v111
	v_cndmask_b32_e32 v103, v202, v103, vcc

; __device__ __forceinline__ int crow(int r, int h) { return (r & 3) + 8 * (r >> 2) + 4 * h; }
;     ...
;                     const int k0 = crow(r, h2), k1 = k0 + 32;
;                     int d0 = k0 - qcl + 15, d1 = k1 - qcl + 15; d0 = d0 < 0 ? 0 : (d0 > 30 ? 30 : d0); d1 = d1 < 0 ? 0 : (d1 > 30 ? 30 : d1);
;                     const float b0 = rpbL[drow + d0], b1 = rpbL[drow + d1];
;                     s0[r] = ((unsigned)(k0 - csl) < 16u) ? s0[r] * C2S + b0 * LOG2E : -1e30f;
	s_waitcnt lgkmcnt(9)
	v_sub_u32_e32 v168, v222, v176
	v_cmp_gt_u32_e32 vcc, 16, v168
	v_mul_f32_e32 v104, s20, v54
	v_mul_f32_e32 v112, s21, v112
	v_add_f32_e32 v104, v104, v112
	v_cndmask_b32_e32 v104, v202, v104, vcc

; __device__ __forceinline__ int crow(int r, int h) { return (r & 3) + 8 * (r >> 2) + 4 * h; }
;     ...
;                     const int k0 = crow(r, h2), k1 = k0 + 32;
;                     int d0 = k0 - qcl + 15, d1 = k1 - qcl + 15; d0 = d0 < 0 ? 0 : (d0 > 30 ? 30 : d0); d1 = d1 < 0 ? 0 : (d1 > 30 ? 30 : d1);
;                     const float b0 = rpbL[drow + d0], b1 = rpbL[drow + d1];
;                     s0[r] = ((unsigned)(k0 - csl) < 16u) ? s0[r] * C2S + b0 * LOG2E : -1e30f;
	s_waitcnt lgkmcnt(8)
	v_sub_u32_e32 v168, v224, v176
	v_cmp_gt_u32_e32 vcc, 16, v168
	v_mul_f32_e32 v105, s20, v55
	v_mul_f32_e32 v113, s21, v113
	v_add_f32_e32 v105, v105, v113
	v_cndmask_b32_e32 v105, v202, v105, vcc

; __device__ __forceinline__ int crow(int r, int h) { return (r & 3) + 8 * (r >> 2) + 4 * h; }
;     ...
;                     const int k0 = crow(r, h2), k1 = k0 + 32;
;                     int d0 = k0 - qcl + 15, d1 = k1 - qcl + 15; d0 = d0 < 0 ? 0 : (d0 > 30 ? 30 : d0); d1 = d1 < 0 ? 0 : (d1 > 30 ? 30 : d1);
;                     const float b0 = rpbL[drow + d0], b1 = rpbL[drow + d1];
;                     s0[r] = ((unsigned)(k0 - csl) < 16u) ? s0[r] * C2S + b0 * LOG2E : -1e30f;
	s_waitcnt lgkmcnt(7)
	v_sub_u32_e32 v168, v226, v176
	v_cmp_gt_u32_e32 vcc, 16, v168
	v_mul_f32_e32 v106, s20, v56
	v_mul_f32_e32 v116, s21, v116
	v_add_f32_e32 v106, v106, v116
	v_cndmask_b32_e32 v106, v202, v106, vcc

; __device__ __forceinline__ int crow(int r, int h) { return (r & 3) + 8 * (r >> 2) + 4 * h; }
;     ...
;                     const int k0 = crow(r, h2), k1 = k0 + 32;
;                     int d0 = k0 - qcl + 15, d1 = k1 - qcl + 15; d0 = d0 < 0 ? 0 : (d0 > 30 ? 30 : d0); d1 = d1 < 0 ? 0 : (d1 > 30 ? 30 : d1);
;                     const float b0 = rpbL[drow + d0], b1 = rpbL[drow + d1];
;                     s0[r] = ((unsigned)(k0 - csl) < 16u) ? s0[r] * C2S + b0 * LOG2E : -1e30f;
	s_waitcnt lgkmcnt(6)
	v_sub_u32_e32 v168, v228, v176
	v_cmp_gt_u32_e32 vcc, 16, v168
	v_mul_f32_e32 v107, s20, v57
	v_mul_f32_e32 v118, s21, v118
	v_add_f32_e32 v107, v107, v118
	v_cndmask_b32_e32 v107, v202, v107, vcc

; __device__ __forceinline__ int crow(int r, int h) { return (r & 3) + 8 * (r >> 2) + 4 * h; }
;     ...
;                     const int k0 = crow(r, h2), k1 = k0 + 32;
;                     int d0 = k0 - qcl + 15, d1 = k1 - qcl + 15; d0 = d0 < 0 ? 0 : (d0 > 30 ? 30 : d0); d1 = d1 < 0 ? 0 : (d1 > 30 ? 30 : d1);
;                     const float b0 = rpbL[drow + d0], b1 = rpbL[drow + d1];
;                     s0[r] = ((unsigned)(k0 - csl) < 16u) ? s0[r] * C2S + b0 * LOG2E : -1e30f;
	s_waitcnt lgkmcnt(5)
	v_sub_u32_e32 v168, v230, v176
	v_cmp_gt_u32_e32 vcc, 16, v168
	v_mul_f32_e32 v108, s20, v58
	v_mul_f32_e32 v120, s21, v120
	v_add_f32_e32 v108, v108, v120
	v_cndmask_b32_e32 v108, v202, v108, vcc

; __device__ __forceinline__ int crow(int r, int h) { return (r & 3) + 8 * (r >> 2) + 4 * h; }
;     ...
;                     const int k0 = crow(r, h2), k1 = k0 + 32;
;                     int d0 = k0 - qcl + 15, d1 = k1 - qcl + 15; d0 = d0 < 0 ? 0 : (d0 > 30 ? 30 : d0); d1 = d1 < 0 ? 0 : (d1 > 30 ? 30 : d1);
;                     const float b0 = rpbL[drow + d0], b1 = rpbL[drow + d1];
;                     s0[r] = ((unsigned)(k0 - csl) < 16u) ? s0[r] * C2S + b0 * LOG2E : -1e30f;
	s_waitcnt lgkmcnt(4)
	v_sub_u32_e32 v168, v232, v176
	v_cmp_gt_u32_e32 vcc, 16, v168
	v_mul_f32_e32 v109, s20, v59
	v_mul_f32_e32 v122, s21, v122
	v_add_f32_e32 v109, v109, v122
	v_cndmask_b32_e32 v109, v202, v109, vcc

; __device__ __forceinline__ int crow(int r, int h) { return (r & 3) + 8 * (r >> 2) + 4 * h; }
;     ...
;                     const int k0 = crow(r, h2), k1 = k0 + 32;
;                     int d0 = k0 - qcl + 15, d1 = k1 - qcl + 15; d0 = d0 < 0 ? 0 : (d0 > 30 ? 30 : d0); d1 = d1 < 0 ? 0 : (d1 > 30 ? 30 : d1);
;                     const float b0 = rpbL[drow + d0], b1 = rpbL[drow + d1];
;                     s0[r] = ((unsigned)(k0 - csl) < 16u) ? s0[r] * C2S + b0 * LOG2E : -1e30f;
	s_waitcnt lgkmcnt(3)
	v_sub_u32_e32 v168, v234, v176
	v_cmp_gt_u32_e32 vcc, 16, v168
	v_mul_f32_e32 v110, s20, v60
	v_mul_f32_e32 v124, s21, v124
	v_add_f32_e32 v110, v110, v124
	v_cndmask_b32_e32 v110, v202, v110, vcc

; __device__ __forceinline__ int crow(int r, int h) { return (r & 3) + 8 * (r >> 2) + 4 * h; }
;     ...
;                     const int k0 = crow(r, h2), k1 = k0 + 32;
;                     int d0 = k0 - qcl + 15, d1 = k1 - qcl + 15; d0 = d0 < 0 ? 0 : (d0 > 30 ? 30 : d0); d1 = d1 < 0 ? 0 : (d1 > 30 ? 30 : d1);
;                     const float b0 = rpbL[drow + d0], b1 = rpbL[drow + d1];
;                     s0[r] = ((unsigned)(k0 - csl) < 16u) ? s0[r] * C2S + b0 * LOG2E : -1e30f;
	s_waitcnt lgkmcnt(2)
	v_sub_u32_e32 v168, v236, v176
	v_cmp_gt_u32_e32 vcc, 16, v168
	v_mul_f32_e32 v111, s20, v61
	v_mul_f32_e32 v126, s21, v126
	v_add_f32_e32 v111, v111, v126
	v_cndmask_b32_e32 v111, v202, v111, vcc

; __device__ __forceinline__ int crow(int r, int h) { return (r & 3) + 8 * (r >> 2) + 4 * h; }
;     ...
;                     const int k0 = crow(r, h2), k1 = k0 + 32;
;                     int d0 = k0 - qcl + 15, d1 = k1 - qcl + 15; d0 = d0 < 0 ? 0 : (d0 > 30 ? 30 : d0); d1 = d1 < 0 ? 0 : (d1 > 30 ? 30 : d1);
;                     const float b0 = rpbL[drow + d0], b1 = rpbL[drow + d1];
;                     s0[r] = ((unsigned)(k0 - csl) < 16u) ? s0[r] * C2S + b0 * LOG2E : -1e30f;
	s_waitcnt lgkmcnt(1)
	v_sub_u32_e32 v168, v238, v176
	v_cmp_gt_u32_e32 vcc, 16, v168
	v_mul_f32_e32 v112, s20, v62
	v_mul_f32_e32 v128, s21, v128
	v_add_f32_e32 v112, v112, v128
	v_cndmask_b32_e32 v112, v202, v112, vcc

; __device__ __forceinline__ int crow(int r, int h) { return (r & 3) + 8 * (r >> 2) + 4 * h; }
;     ...
;                     const int k0 = crow(r, h2), k1 = k0 + 32;
;                     int d0 = k0 - qcl + 15, d1 = k1 - qcl + 15; d0 = d0 < 0 ? 0 : (d0 > 30 ? 30 : d0); d1 = d1 < 0 ? 0 : (d1 > 30 ? 30 : d1);
;                     const float b0 = rpbL[drow + d0], b1 = rpbL[drow + d1];
;                     s0[r] = ((unsigned)(k0 - csl) < 16u) ? s0[r] * C2S + b0 * LOG2E : -1e30f;
	s_waitcnt lgkmcnt(0)
	v_sub_u32_e32 v168, v240, v176
	v_cmp_gt_u32_e32 vcc, 16, v168
	v_mul_f32_e32 v113, s20, v63
	v_mul_f32_e32 v164, s21, v164
	v_add_f32_e32 v113, v113, v164
	v_cndmask_b32_e32 v113, v202, v113, vcc

; __device__ __forceinline__ int crow(int r, int h) { return (r & 3) + 8 * (r >> 2) + 4 * h; }
;     ...
;                 for (int r = 0; r < 16; ++r) {
;                     const int k0 = crow(r, h2), k1 = k0 + 32;
;                     int d0 = k0 - qcl + 15, d1 = k1 - qcl + 15; d0 = d0 < 0 ? 0 : (d0 > 30 ? 30 : d0); d1 = d1 < 0 ? 0 : (d1 > 30 ? 30 : d1);
;                     const float b0 = rpbL[drow + d0], b1 = rpbL[drow + d1];
;                     s0[r] = ((unsigned)(k0 - csl) < 16u) ? s0[r] * C2S + b0 * LOG2E : -1e30f;
;                     s1[r] = ((unsigned)(k1 - csl) < 16u) ? s1[r] * C2S + b1 * LOG2E : -1e30f;
	ds_read_b32 v115, v166 offset:128
	ds_read_b32 v117, v166 offset:132
	ds_read_b32 v119, v166 offset:136
	ds_read_b32 v121, v166 offset:140
	ds_read_b32 v123, v166 offset:160
	ds_read_b32 v125, v166 offset:164
	ds_read_b32 v127, v166 offset:168
	ds_read_b32 v129, v166 offset:172
	ds_read_b32 v165, v166 offset:192
	ds_read_b32 v167, v166 offset:196
	ds_read_b32 v169, v166 offset:200
	ds_read_b32 v171, v166 offset:204
	ds_read_b32 v173, v166 offset:224
	ds_read_b32 v175, v166 offset:228
	ds_read_b32 v179, v166 offset:232
	ds_read_b32 v177, v166 offset:236
	v_sub_u32_e32 v114, v211, v176
	v_cmp_gt_u32_e32 vcc, 16, v114
	v_mov_b32_e32 v114, v32
	s_waitcnt lgkmcnt(14)
	v_pk_mul_f32 v[114:115], v[114:115], s[20:21]
	v_mov_b32_e32 v116, v33
	v_add_f32_e32 v114, v114, v115
	v_sub_u32_e32 v115, v213, v176
	v_pk_mul_f32 v[116:117], v[116:117], s[20:21]
	v_cndmask_b32_e32 v114, v202, v114, vcc
	v_cmp_gt_u32_e32 vcc, 16, v115
	v_add_f32_e32 v115, v116, v117
	v_sub_u32_e32 v116, v215, v176
	v_mov_b32_e32 v118, v34
	v_cndmask_b32_e32 v115, v202, v115, vcc
	v_cmp_gt_u32_e32 vcc, 16, v116
	s_waitcnt lgkmcnt(13)
	v_pk_mul_f32 v[116:117], v[118:119], s[20:21]
	v_mov_b32_e32 v120, v35
	v_add_f32_e32 v116, v116, v117
	v_sub_u32_e32 v117, v217, v176
	s_waitcnt lgkmcnt(12)
	v_pk_mul_f32 v[118:119], v[120:121], s[20:21]
	v_cndmask_b32_e32 v116, v202, v116, vcc
	v_cmp_gt_u32_e32 vcc, 16, v117
	v_add_f32_e32 v117, v118, v119
	v_sub_u32_e32 v118, v219, v176
	v_mov_b32_e32 v122, v36
	v_cndmask_b32_e32 v117, v202, v117, vcc
	v_cmp_gt_u32_e32 vcc, 16, v118
	s_waitcnt lgkmcnt(11)
	v_pk_mul_f32 v[118:119], v[122:123], s[20:21]
	v_mov_b32_e32 v124, v37
	v_add_f32_e32 v118, v118, v119
	v_sub_u32_e32 v119, v221, v176
	s_waitcnt lgkmcnt(10)
	v_pk_mul_f32 v[120:121], v[124:125], s[20:21]
	v_cndmask_b32_e32 v118, v202, v118, vcc
	v_cmp_gt_u32_e32 vcc, 16, v119
	v_add_f32_e32 v119, v120, v121
	v_sub_u32_e32 v120, v223, v176
	v_mov_b32_e32 v126, v38
	v_cndmask_b32_e32 v119, v202, v119, vcc
	v_cmp_gt_u32_e32 vcc, 16, v120
	s_waitcnt lgkmcnt(9)
	v_pk_mul_f32 v[120:121], v[126:127], s[20:21]
	v_mov_b32_e32 v128, v39
	v_add_f32_e32 v120, v120, v121
	v_sub_u32_e32 v121, v225, v176
	s_waitcnt lgkmcnt(8)
	v_pk_mul_f32 v[122:123], v[128:129], s[20:21]
	v_cndmask_b32_e32 v120, v202, v120, vcc
	v_cmp_gt_u32_e32 vcc, 16, v121
	v_add_f32_e32 v121, v122, v123
	v_sub_u32_e32 v122, v227, v176
	v_mov_b32_e32 v164, v40
	v_cndmask_b32_e32 v121, v202, v121, vcc
	v_cmp_gt_u32_e32 vcc, 16, v122
	s_waitcnt lgkmcnt(7)
	v_pk_mul_f32 v[122:123], v[164:165], s[20:21]
	v_mov_b32_e32 v166, v41
	v_add_f32_e32 v122, v122, v123
	v_sub_u32_e32 v123, v229, v176
	s_waitcnt lgkmcnt(6)
	v_pk_mul_f32 v[124:125], v[166:167], s[20:21]
	v_cndmask_b32_e32 v122, v202, v122, vcc
	v_cmp_gt_u32_e32 vcc, 16, v123
	v_add_f32_e32 v123, v124, v125
	v_sub_u32_e32 v124, v231, v176
	v_mov_b32_e32 v168, v42
	v_cndmask_b32_e32 v123, v202, v123, vcc
	v_cmp_gt_u32_e32 vcc, 16, v124
	s_waitcnt lgkmcnt(5)
	v_pk_mul_f32 v[124:125], v[168:169], s[20:21]
	v_mov_b32_e32 v170, v43
	v_add_f32_e32 v124, v124, v125
	v_sub_u32_e32 v125, v233, v176
	s_waitcnt lgkmcnt(4)
	v_pk_mul_f32 v[126:127], v[170:171], s[20:21]
	v_cndmask_b32_e32 v124, v202, v124, vcc
	v_cmp_gt_u32_e32 vcc, 16, v125
	v_add_f32_e32 v125, v126, v127
	v_sub_u32_e32 v126, v235, v176
	v_mov_b32_e32 v172, v44
	v_cndmask_b32_e32 v125, v202, v125, vcc
	v_cmp_gt_u32_e32 vcc, 16, v126
	s_waitcnt lgkmcnt(3)
	v_pk_mul_f32 v[126:127], v[172:173], s[20:21]
	v_mov_b32_e32 v174, v45
	v_add_f32_e32 v126, v126, v127
	v_sub_u32_e32 v127, v237, v176
	s_waitcnt lgkmcnt(2)
	v_pk_mul_f32 v[128:129], v[174:175], s[20:21]
	v_cndmask_b32_e32 v126, v202, v126, vcc
	v_cmp_gt_u32_e32 vcc, 16, v127
	v_add_f32_e32 v127, v128, v129
	v_sub_u32_e32 v128, v239, v176
	v_mov_b32_e32 v178, v46
	v_cndmask_b32_e32 v127, v202, v127, vcc
	v_cmp_gt_u32_e32 vcc, 16, v128
	s_waitcnt lgkmcnt(1)
	v_pk_mul_f32 v[128:129], v[178:179], s[20:21]
	s_mov_b64 s[48:49], -1
	v_add_f32_e32 v128, v128, v129
	v_sub_u32_e32 v129, v241, v176
	v_mov_b32_e32 v176, v47
	s_waitcnt lgkmcnt(0)
	v_pk_mul_f32 v[164:165], v[176:177], s[20:21]
	v_cndmask_b32_e32 v128, v202, v128, vcc
	v_cmp_gt_u32_e32 vcc, 16, v129
	v_add_f32_e32 v129, v164, v165
	s_nop 0
	v_cndmask_b32_e32 v129, v202, v129, vcc

;     ...
;             if (biased) {
;                 const int drow = (kr0 + t - qr + 7) * 32;
;                 int qcl = qc, csl = cs; asm volatile("" : "+v"(qcl), "+v"(csl));
.LBB0_532:
	v_readlane_b32 s78, v255, 2
	s_andn2_b64 vcc, exec, s[2:3]
	s_mov_b64 s[48:49], 0
	v_readlane_b32 s79, v255, 3
	s_cbranch_vccnz .LBB0_566
	v_mov_b32_e32 v114, v192
	v_mov_b32_e32 v167, v193
	s_add_i32 s4, s70, s71

; __device__ __forceinline__ int crow(int r, int h) { return (r & 3) + 8 * (r >> 2) + 4 * h; }
;     ...
;                     const int k0 = crow(r, h2), k1 = k0 + 32;
;                     int d0 = k0 - qcl + 15, d1 = k1 - qcl + 15; d0 = d0 < 0 ? 0 : (d0 > 30 ? 30 : d0); d1 = d1 < 0 ? 0 : (d1 > 30 ? 30 : d1);
;                     const float b0 = rpbL[drow + d0], b1 = rpbL[drow + d1];
	v_sub_u32_e32 v168, v188, v114
	v_lshl_add_u32 v168, v168, 2, s4
	v_add_u32_e32 v168, 0xb03c, v168

; __device__ __forceinline__ int crow(int r, int h) { return (r & 3) + 8 * (r >> 2) + 4 * h; }
;     ...
;                     const int k0 = crow(r, h2), k1 = k0 + 32;
;                     int d0 = k0 - qcl + 15, d1 = k1 - qcl + 15; d0 = d0 < 0 ? 0 : (d0 > 30 ? 30 : d0); d1 = d1 < 0 ? 0 : (d1 > 30 ? 30 : d1);
;                     const float b0 = rpbL[drow + d0], b1 = rpbL[drow + d1];
;                     s0[r] = ((unsigned)(k0 - csl) < 16u) ? s0[r] * C2S + b0 * LOG2E : -1e30f;
	ds_read_b32 v98, v168
	ds_read_b32 v99, v168 offset:4
	ds_read_b32 v100, v168 offset:8
	ds_read_b32 v101, v168 offset:12
	ds_read_b32 v102, v168 offset:32
	ds_read_b32 v103, v168 offset:36
	ds_read_b32 v104, v168 offset:40
	ds_read_b32 v105, v168 offset:44
	ds_read_b32 v106, v168 offset:64
	ds_read_b32 v107, v168 offset:68
	ds_read_b32 v108, v168 offset:72
	ds_read_b32 v109, v168 offset:76
	ds_read_b32 v110, v168 offset:96
	ds_read_b32 v111, v168 offset:100
	ds_read_b32 v112, v168 offset:104
	ds_read_b32 v113, v168 offset:108
	s_waitcnt lgkmcnt(15)
	v_sub_u32_e32 v169, v188, v167
	v_cmp_gt_u32_e32 vcc, 16, v169
	v_mul_f32_e32 v98, s21, v98
	v_mul_f32_e32 v168, s20, v82
	v_add_f32_e32 v98, v168, v98
	v_cndmask_b32_e32 v98, v202, v98, vcc

; __device__ __forceinline__ int crow(int r, int h) { return (r & 3) + 8 * (r >> 2) + 4 * h; }
;     ...
;                     const int k0 = crow(r, h2), k1 = k0 + 32;
;                     int d0 = k0 - qcl + 15, d1 = k1 - qcl + 15; d0 = d0 < 0 ? 0 : (d0 > 30 ? 30 : d0); d1 = d1 < 0 ? 0 : (d1 > 30 ? 30 : d1);
;                     const float b0 = rpbL[drow + d0], b1 = rpbL[drow + d1];
;                     s0[r] = ((unsigned)(k0 - csl) < 16u) ? s0[r] * C2S + b0 * LOG2E : -1e30f;
	s_waitcnt lgkmcnt(14)
	v_sub_u32_e32 v169, v212, v167
	v_cmp_gt_u32_e32 vcc, 16, v169
	v_mul_f32_e32 v99, s21, v99
	v_mul_f32_e32 v168, s20, v83
	v_add_f32_e32 v99, v168, v99
	v_cndmask_b32_e32 v99, v202, v99, vcc

; __device__ __forceinline__ int crow(int r, int h) { return (r & 3) + 8 * (r >> 2) + 4 * h; }
;     ...
;                     const int k0 = crow(r, h2), k1 = k0 + 32;
;                     int d0 = k0 - qcl + 15, d1 = k1 - qcl + 15; d0 = d0 < 0 ? 0 : (d0 > 30 ? 30 : d0); d1 = d1 < 0 ? 0 : (d1 > 30 ? 30 : d1);
;                     const float b0 = rpbL[drow + d0], b1 = rpbL[drow + d1];
;                     s0[r] = ((unsigned)(k0 - csl) < 16u) ? s0[r] * C2S + b0 * LOG2E : -1e30f;
	s_waitcnt lgkmcnt(13)
	v_sub_u32_e32 v169, v214, v167
	v_cmp_gt_u32_e32 vcc, 16, v169
	v_mul_f32_e32 v100, s21, v100
	v_mul_f32_e32 v168, s20, v84
	v_add_f32_e32 v100, v168, v100
	v_cndmask_b32_e32 v100, v202, v100, vcc

; __device__ __forceinline__ int crow(int r, int h) { return (r & 3) + 8 * (r >> 2) + 4 * h; }
;     ...
;                     const int k0 = crow(r, h2), k1 = k0 + 32;
;                     int d0 = k0 - qcl + 15, d1 = k1 - qcl + 15; d0 = d0 < 0 ? 0 : (d0 > 30 ? 30 : d0); d1 = d1 < 0 ? 0 : (d1 > 30 ? 30 : d1);
;                     const float b0 = rpbL[drow + d0], b1 = rpbL[drow + d1];
;                     s0[r] = ((unsigned)(k0 - csl) < 16u) ? s0[r] * C2S + b0 * LOG2E : -1e30f;
	s_waitcnt lgkmcnt(12)
	v_sub_u32_e32 v169, v216, v167
	v_cmp_gt_u32_e32 vcc, 16, v169
	v_mul_f32_e32 v101, s21, v101
	v_mul_f32_e32 v168, s20, v85
	v_add_f32_e32 v101, v168, v101
	v_cndmask_b32_e32 v101, v202, v101, vcc

; __device__ __forceinline__ int crow(int r, int h) { return (r & 3) + 8 * (r >> 2) + 4 * h; }
;     ...
;                     const int k0 = crow(r, h2), k1 = k0 + 32;
;                     int d0 = k0 - qcl + 15, d1 = k1 - qcl + 15; d0 = d0 < 0 ? 0 : (d0 > 30 ? 30 : d0); d1 = d1 < 0 ? 0 : (d1 > 30 ? 30 : d1);
;                     const float b0 = rpbL[drow + d0], b1 = rpbL[drow + d1];
;                     s0[r] = ((unsigned)(k0 - csl) < 16u) ? s0[r] * C2S + b0 * LOG2E : -1e30f;
	s_waitcnt lgkmcnt(11)
	v_sub_u32_e32 v169, v218, v167
	v_cmp_gt_u32_e32 vcc, 16, v169
	v_mul_f32_e32 v102, s21, v102
	v_mul_f32_e32 v168, s20, v86
	v_add_f32_e32 v102, v168, v102
	v_cndmask_b32_e32 v102, v202, v102, vcc

; __device__ __forceinline__ int crow(int r, int h) { return (r & 3) + 8 * (r >> 2) + 4 * h; }
;     ...
;                     const int k0 = crow(r, h2), k1 = k0 + 32;
;                     int d0 = k0 - qcl + 15, d1 = k1 - qcl + 15; d0 = d0 < 0 ? 0 : (d0 > 30 ? 30 : d0); d1 = d1 < 0 ? 0 : (d1 > 30 ? 30 : d1);
;                     const float b0 = rpbL[drow + d0], b1 = rpbL[drow + d1];
;                     s0[r] = ((unsigned)(k0 - csl) < 16u) ? s0[r] * C2S + b0 * LOG2E : -1e30f;
	s_waitcnt lgkmcnt(10)
	v_sub_u32_e32 v169, v220, v167
	v_cmp_gt_u32_e32 vcc, 16, v169
	v_mul_f32_e32 v103, s21, v103
	v_mul_f32_e32 v168, s20, v87
	v_add_f32_e32 v103, v168, v103
	v_cndmask_b32_e32 v103, v202, v103, vcc

; __device__ __forceinline__ int crow(int r, int h) { return (r & 3) + 8 * (r >> 2) + 4 * h; }
;     ...
;                     const int k0 = crow(r, h2), k1 = k0 + 32;
;                     int d0 = k0 - qcl + 15, d1 = k1 - qcl + 15; d0 = d0 < 0 ? 0 : (d0 > 30 ? 30 : d0); d1 = d1 < 0 ? 0 : (d1 > 30 ? 30 : d1);
;                     const float b0 = rpbL[drow + d0], b1 = rpbL[drow + d1];
;                     s0[r] = ((unsigned)(k0 - csl) < 16u) ? s0[r] * C2S + b0 * LOG2E : -1e30f;
	s_waitcnt lgkmcnt(9)
	v_sub_u32_e32 v169, v222, v167
	v_cmp_gt_u32_e32 vcc, 16, v169
	v_mul_f32_e32 v104, s21, v104
	v_mul_f32_e32 v168, s20, v88
	v_add_f32_e32 v104, v168, v104
	v_cndmask_b32_e32 v104, v202, v104, vcc

; __device__ __forceinline__ int crow(int r, int h) { return (r & 3) + 8 * (r >> 2) + 4 * h; }
;     ...
;                     const int k0 = crow(r, h2), k1 = k0 + 32;
;                     int d0 = k0 - qcl + 15, d1 = k1 - qcl + 15; d0 = d0 < 0 ? 0 : (d0 > 30 ? 30 : d0); d1 = d1 < 0 ? 0 : (d1 > 30 ? 30 : d1);
;                     const float b0 = rpbL[drow + d0], b1 = rpbL[drow + d1];
;                     s0[r] = ((unsigned)(k0 - csl) < 16u) ? s0[r] * C2S + b0 * LOG2E : -1e30f;
	s_waitcnt lgkmcnt(8)
	v_sub_u32_e32 v169, v224, v167
	v_cmp_gt_u32_e32 vcc, 16, v169
	v_mul_f32_e32 v105, s21, v105
	v_mul_f32_e32 v168, s20, v89
	v_add_f32_e32 v105, v168, v105
	v_cndmask_b32_e32 v105, v202, v105, vcc

; __device__ __forceinline__ int crow(int r, int h) { return (r & 3) + 8 * (r >> 2) + 4 * h; }
;     ...
;                     const int k0 = crow(r, h2), k1 = k0 + 32;
;                     int d0 = k0 - qcl + 15, d1 = k1 - qcl + 15; d0 = d0 < 0 ? 0 : (d0 > 30 ? 30 : d0); d1 = d1 < 0 ? 0 : (d1 > 30 ? 30 : d1);
;                     const float b0 = rpbL[drow + d0], b1 = rpbL[drow + d1];
;                     s0[r] = ((unsigned)(k0 - csl) < 16u) ? s0[r] * C2S + b0 * LOG2E : -1e30f;
	s_waitcnt lgkmcnt(7)
	v_sub_u32_e32 v169, v226, v167
	v_cmp_gt_u32_e32 vcc, 16, v169
	v_mul_f32_e32 v106, s21, v106
	v_mul_f32_e32 v168, s20, v90
	v_add_f32_e32 v106, v168, v106
	v_cndmask_b32_e32 v106, v202, v106, vcc

; __device__ __forceinline__ int crow(int r, int h) { return (r & 3) + 8 * (r >> 2) + 4 * h; }
;     ...
;                     const int k0 = crow(r, h2), k1 = k0 + 32;
;                     int d0 = k0 - qcl + 15, d1 = k1 - qcl + 15; d0 = d0 < 0 ? 0 : (d0 > 30 ? 30 : d0); d1 = d1 < 0 ? 0 : (d1 > 30 ? 30 : d1);
;                     const float b0 = rpbL[drow + d0], b1 = rpbL[drow + d1];
;                     s0[r] = ((unsigned)(k0 - csl) < 16u) ? s0[r] * C2S + b0 * LOG2E : -1e30f;
	s_waitcnt lgkmcnt(6)
	v_sub_u32_e32 v169, v228, v167
	v_cmp_gt_u32_e32 vcc, 16, v169
	v_mul_f32_e32 v107, s21, v107
	v_mul_f32_e32 v168, s20, v91
	v_add_f32_e32 v107, v168, v107
	v_cndmask_b32_e32 v107, v202, v107, vcc

; __device__ __forceinline__ int crow(int r, int h) { return (r & 3) + 8 * (r >> 2) + 4 * h; }
;     ...
;                     const int k0 = crow(r, h2), k1 = k0 + 32;
;                     int d0 = k0 - qcl + 15, d1 = k1 - qcl + 15; d0 = d0 < 0 ? 0 : (d0 > 30 ? 30 : d0); d1 = d1 < 0 ? 0 : (d1 > 30 ? 30 : d1);
;                     const float b0 = rpbL[drow + d0], b1 = rpbL[drow + d1];
;                     s0[r] = ((unsigned)(k0 - csl) < 16u) ? s0[r] * C2S + b0 * LOG2E : -1e30f;
	s_waitcnt lgkmcnt(5)
	v_sub_u32_e32 v169, v230, v167
	v_cmp_gt_u32_e32 vcc, 16, v169
	v_mul_f32_e32 v108, s21, v108
	v_mul_f32_e32 v168, s20, v92
	v_add_f32_e32 v108, v168, v108
	v_cndmask_b32_e32 v108, v202, v108, vcc

; __device__ __forceinline__ int crow(int r, int h) { return (r & 3) + 8 * (r >> 2) + 4 * h; }
;     ...
;                     const int k0 = crow(r, h2), k1 = k0 + 32;
;                     int d0 = k0 - qcl + 15, d1 = k1 - qcl + 15; d0 = d0 < 0 ? 0 : (d0 > 30 ? 30 : d0); d1 = d1 < 0 ? 0 : (d1 > 30 ? 30 : d1);
;                     const float b0 = rpbL[drow + d0], b1 = rpbL[drow + d1];
;                     s0[r] = ((unsigned)(k0 - csl) < 16u) ? s0[r] * C2S + b0 * LOG2E : -1e30f;
	s_waitcnt lgkmcnt(4)
	v_sub_u32_e32 v169, v232, v167
	v_cmp_gt_u32_e32 vcc, 16, v169
	v_mul_f32_e32 v109, s21, v109
	v_mul_f32_e32 v168, s20, v93
	v_add_f32_e32 v109, v168, v109
	v_cndmask_b32_e32 v109, v202, v109, vcc

; __device__ __forceinline__ int crow(int r, int h) { return (r & 3) + 8 * (r >> 2) + 4 * h; }
;     ...
;                     const int k0 = crow(r, h2), k1 = k0 + 32;
;                     int d0 = k0 - qcl + 15, d1 = k1 - qcl + 15; d0 = d0 < 0 ? 0 : (d0 > 30 ? 30 : d0); d1 = d1 < 0 ? 0 : (d1 > 30 ? 30 : d1);
;                     const float b0 = rpbL[drow + d0], b1 = rpbL[drow + d1];
;                     s0[r] = ((unsigned)(k0 - csl) < 16u) ? s0[r] * C2S + b0 * LOG2E : -1e30f;
	s_waitcnt lgkmcnt(3)
	v_sub_u32_e32 v169, v234, v167
	v_cmp_gt_u32_e32 vcc, 16, v169
	v_mul_f32_e32 v110, s21, v110
	v_mul_f32_e32 v168, s20, v94
	v_add_f32_e32 v110, v168, v110
	v_cndmask_b32_e32 v110, v202, v110, vcc

; __device__ __forceinline__ int crow(int r, int h) { return (r & 3) + 8 * (r >> 2) + 4 * h; }
;     ...
;                     const int k0 = crow(r, h2), k1 = k0 + 32;
;                     int d0 = k0 - qcl + 15, d1 = k1 - qcl + 15; d0 = d0 < 0 ? 0 : (d0 > 30 ? 30 : d0); d1 = d1 < 0 ? 0 : (d1 > 30 ? 30 : d1);
;                     const float b0 = rpbL[drow + d0], b1 = rpbL[drow + d1];
;                     s0[r] = ((unsigned)(k0 - csl) < 16u) ? s0[r] * C2S + b0 * LOG2E : -1e30f;
	s_waitcnt lgkmcnt(2)
	v_sub_u32_e32 v169, v236, v167
	v_cmp_gt_u32_e32 vcc, 16, v169
	v_mul_f32_e32 v111, s21, v111
	v_mul_f32_e32 v168, s20, v95
	v_add_f32_e32 v111, v168, v111
	v_cndmask_b32_e32 v111, v202, v111, vcc

; __device__ __forceinline__ int crow(int r, int h) { return (r & 3) + 8 * (r >> 2) + 4 * h; }
;     ...
;                     const int k0 = crow(r, h2), k1 = k0 + 32;
;                     int d0 = k0 - qcl + 15, d1 = k1 - qcl + 15; d0 = d0 < 0 ? 0 : (d0 > 30 ? 30 : d0); d1 = d1 < 0 ? 0 : (d1 > 30 ? 30 : d1);
;                     const float b0 = rpbL[drow + d0], b1 = rpbL[drow + d1];
;                     s0[r] = ((unsigned)(k0 - csl) < 16u) ? s0[r] * C2S + b0 * LOG2E : -1e30f;
	s_waitcnt lgkmcnt(1)
	v_sub_u32_e32 v169, v238, v167
	v_cmp_gt_u32_e32 vcc, 16, v169
	v_mul_f32_e32 v112, s21, v112
	v_mul_f32_e32 v168, s20, v96
	v_add_f32_e32 v112, v168, v112
	v_cndmask_b32_e32 v112, v202, v112, vcc

; __device__ __forceinline__ int crow(int r, int h) { return (r & 3) + 8 * (r >> 2) + 4 * h; }
;     ...
;                     const int k0 = crow(r, h2), k1 = k0 + 32;
;                     int d0 = k0 - qcl + 15, d1 = k1 - qcl + 15; d0 = d0 < 0 ? 0 : (d0 > 30 ? 30 : d0); d1 = d1 < 0 ? 0 : (d1 > 30 ? 30 : d1);
;                     const float b0 = rpbL[drow + d0], b1 = rpbL[drow + d1];
;                     s0[r] = ((unsigned)(k0 - csl) < 16u) ? s0[r] * C2S + b0 * LOG2E : -1e30f;
	s_waitcnt lgkmcnt(0)
	v_sub_u32_e32 v169, v240, v167
	v_cmp_gt_u32_e32 vcc, 16, v169
	v_mul_f32_e32 v113, s21, v113
	v_mul_f32_e32 v168, s20, v97
	v_add_f32_e32 v113, v168, v113
	v_cndmask_b32_e32 v113, v202, v113, vcc

; __device__ __forceinline__ int crow(int r, int h) { return (r & 3) + 8 * (r >> 2) + 4 * h; }
;     ...
;                     const int k0 = crow(r, h2), k1 = k0 + 32;
;                     int d0 = k0 - qcl + 15, d1 = k1 - qcl + 15; d0 = d0 < 0 ? 0 : (d0 > 30 ? 30 : d0); d1 = d1 < 0 ? 0 : (d1 > 30 ? 30 : d1);
;                     const float b0 = rpbL[drow + d0], b1 = rpbL[drow + d1];
	v_sub_u32_e32 v82, v188, v114
	v_lshl_add_u32 v82, v82, 2, s4
	v_add_u32_e32 v82, 0xb03c, v82

; __device__ __forceinline__ int crow(int r, int h) { return (r & 3) + 8 * (r >> 2) + 4 * h; }
;     ...
;                 for (int r = 0; r < 16; ++r) {
;                     const int k0 = crow(r, h2), k1 = k0 + 32;
;                     int d0 = k0 - qcl + 15, d1 = k1 - qcl + 15; d0 = d0 < 0 ? 0 : (d0 > 30 ? 30 : d0); d1 = d1 < 0 ? 0 : (d1 > 30 ? 30 : d1);
;                     const float b0 = rpbL[drow + d0], b1 = rpbL[drow + d1];
;                     s0[r] = ((unsigned)(k0 - csl) < 16u) ? s0[r] * C2S + b0 * LOG2E : -1e30f;
;                     s1[r] = ((unsigned)(k1 - csl) < 16u) ? s1[r] * C2S + b1 * LOG2E : -1e30f;
	ds_read_b32 v115, v82 offset:128
	ds_read_b32 v117, v82 offset:132
	ds_read_b32 v83, v82 offset:136
	ds_read_b32 v119, v82 offset:140
	ds_read_b32 v85, v82 offset:160
	ds_read_b32 v121, v82 offset:164
	ds_read_b32 v87, v82 offset:168
	ds_read_b32 v123, v82 offset:172
	ds_read_b32 v89, v82 offset:192
	ds_read_b32 v125, v82 offset:196
	ds_read_b32 v91, v82 offset:200
	ds_read_b32 v127, v82 offset:204
	ds_read_b32 v93, v82 offset:224
	ds_read_b32 v129, v82 offset:228
	ds_read_b32 v165, v82 offset:232
	ds_read_b32 v95, v82 offset:236
	v_mov_b32_e32 v114, v66
	v_sub_u32_e32 v82, v211, v167
	s_waitcnt lgkmcnt(14)
	v_pk_mul_f32 v[96:97], v[114:115], s[20:21]
	v_mov_b32_e32 v116, v67
	v_cmp_gt_u32_e32 vcc, 16, v82
	v_add_f32_e32 v66, v96, v97
	v_sub_u32_e32 v82, v213, v167
	v_pk_mul_f32 v[96:97], v[116:117], s[20:21]
	v_cndmask_b32_e32 v66, v202, v66, vcc
	v_cmp_gt_u32_e32 vcc, 16, v82
	v_add_f32_e32 v67, v96, v97
	v_sub_u32_e32 v82, v215, v167
	v_cndmask_b32_e32 v67, v202, v67, vcc
	v_cmp_gt_u32_e32 vcc, 16, v82
	v_mov_b32_e32 v82, v68
	s_waitcnt lgkmcnt(13)
	v_pk_mul_f32 v[82:83], v[82:83], s[20:21]
	v_mov_b32_e32 v118, v69
	v_add_f32_e32 v68, v82, v83
	v_sub_u32_e32 v82, v217, v167
	v_cndmask_b32_e32 v68, v202, v68, vcc
	v_cmp_gt_u32_e32 vcc, 16, v82
	s_waitcnt lgkmcnt(12)
	v_pk_mul_f32 v[82:83], v[118:119], s[20:21]
	v_mov_b32_e32 v84, v70
	v_add_f32_e32 v69, v82, v83
	v_sub_u32_e32 v82, v219, v167
	v_cndmask_b32_e32 v69, v202, v69, vcc
	v_cmp_gt_u32_e32 vcc, 16, v82
	s_waitcnt lgkmcnt(11)
	v_pk_mul_f32 v[82:83], v[84:85], s[20:21]
	v_mov_b32_e32 v120, v71
	v_add_f32_e32 v70, v82, v83
	v_sub_u32_e32 v82, v221, v167
	v_cndmask_b32_e32 v70, v202, v70, vcc
	v_cmp_gt_u32_e32 vcc, 16, v82
	s_waitcnt lgkmcnt(10)
	v_pk_mul_f32 v[82:83], v[120:121], s[20:21]
	v_mov_b32_e32 v86, v72
	v_add_f32_e32 v71, v82, v83
	v_sub_u32_e32 v82, v223, v167
	v_cndmask_b32_e32 v71, v202, v71, vcc
	v_cmp_gt_u32_e32 vcc, 16, v82
	s_waitcnt lgkmcnt(9)
	v_pk_mul_f32 v[82:83], v[86:87], s[20:21]
	v_mov_b32_e32 v122, v73
	v_add_f32_e32 v72, v82, v83
	v_sub_u32_e32 v82, v225, v167
	v_cndmask_b32_e32 v72, v202, v72, vcc
	v_cmp_gt_u32_e32 vcc, 16, v82
	s_waitcnt lgkmcnt(8)
	v_pk_mul_f32 v[82:83], v[122:123], s[20:21]
	v_mov_b32_e32 v88, v74
	v_add_f32_e32 v73, v82, v83
	v_sub_u32_e32 v82, v227, v167
	v_cndmask_b32_e32 v73, v202, v73, vcc
	v_cmp_gt_u32_e32 vcc, 16, v82
	s_waitcnt lgkmcnt(7)
	v_pk_mul_f32 v[82:83], v[88:89], s[20:21]
	v_mov_b32_e32 v124, v75
	v_add_f32_e32 v74, v82, v83
	v_sub_u32_e32 v82, v229, v167
	v_cndmask_b32_e32 v74, v202, v74, vcc
	v_cmp_gt_u32_e32 vcc, 16, v82
	s_waitcnt lgkmcnt(6)
	v_pk_mul_f32 v[82:83], v[124:125], s[20:21]
	v_mov_b32_e32 v90, v76
	v_add_f32_e32 v75, v82, v83
	v_sub_u32_e32 v82, v231, v167
	v_cndmask_b32_e32 v75, v202, v75, vcc
	v_cmp_gt_u32_e32 vcc, 16, v82
	s_waitcnt lgkmcnt(5)
	v_pk_mul_f32 v[82:83], v[90:91], s[20:21]
	v_mov_b32_e32 v126, v77
	v_add_f32_e32 v76, v82, v83
	v_sub_u32_e32 v82, v233, v167
	v_cndmask_b32_e32 v76, v202, v76, vcc
	v_cmp_gt_u32_e32 vcc, 16, v82
	s_waitcnt lgkmcnt(4)
	v_pk_mul_f32 v[82:83], v[126:127], s[20:21]
	v_mov_b32_e32 v92, v78
	v_add_f32_e32 v77, v82, v83
	v_sub_u32_e32 v82, v235, v167
	v_cndmask_b32_e32 v77, v202, v77, vcc
	v_cmp_gt_u32_e32 vcc, 16, v82
	s_waitcnt lgkmcnt(3)
	v_pk_mul_f32 v[82:83], v[92:93], s[20:21]
	v_mov_b32_e32 v128, v79
	v_add_f32_e32 v78, v82, v83
	v_sub_u32_e32 v82, v237, v167
	v_cndmask_b32_e32 v78, v202, v78, vcc
	v_cmp_gt_u32_e32 vcc, 16, v82
	s_waitcnt lgkmcnt(2)
	v_pk_mul_f32 v[82:83], v[128:129], s[20:21]
	v_mov_b32_e32 v164, v80
	v_add_f32_e32 v79, v82, v83
	v_sub_u32_e32 v82, v239, v167
	v_cndmask_b32_e32 v79, v202, v79, vcc
	v_cmp_gt_u32_e32 vcc, 16, v82
	s_waitcnt lgkmcnt(1)
	v_pk_mul_f32 v[82:83], v[164:165], s[20:21]
	v_mov_b32_e32 v94, v81
	v_add_f32_e32 v80, v82, v83
	v_sub_u32_e32 v82, v241, v167
	v_cndmask_b32_e32 v80, v202, v80, vcc
	v_cmp_gt_u32_e32 vcc, 16, v82
	s_waitcnt lgkmcnt(0)
	v_pk_mul_f32 v[82:83], v[94:95], s[20:21]
	s_mov_b64 s[48:49], -1
	v_add_f32_e32 v81, v82, v83
	v_mov_b64_e32 v[82:83], v[98:99]
	v_cndmask_b32_e32 v81, v202, v81, vcc
	v_mov_b64_e32 v[84:85], v[100:101]
	v_mov_b64_e32 v[86:87], v[102:103]
	v_mov_b64_e32 v[88:89], v[104:105]
	v_mov_b64_e32 v[90:91], v[106:107]
	v_mov_b64_e32 v[92:93], v[108:109]
	v_mov_b64_e32 v[94:95], v[110:111]
	v_mov_b64_e32 v[96:97], v[112:113]
